# GEMM K-loop: dropped the mid-run s_setprio 0/1 pairs (one priority bracket per 32-MFMA run)
# speedup vs baseline: 1.0102x; 1.0102x over previous
; #define PG8_STAGE(bufoff, gbase, voff) do { _Pragma("unroll") for (int _i = 0; _i < 2; ++_i) \
;         __builtin_amdgcn_global_load_lds((const unsigned*)((const char*)(gbase) + (voff)[_i]), (PG8_LAS unsigned*)(lds + (bufoff) + ldsw + _i * 8192), 16, 0, 0); } while (0)
; #define PG8_LDA(dst, b, h) do { _Pragma("unroll") for (int m = 0; m < 4; ++m) _Pragma("unroll") for (int k = 0; k < 2; ++k) dst[m][k] = *(const PG8_LAS bf16x8*)(lds + PG8_SA(b, h) + aoff + m * 2048 + k * 1024); } while (0)
; #define PG8_LDB(dst, b, h) do { _Pragma("unroll") for (int n = 0; n < 2; ++n) _Pragma("unroll") for (int k = 0; k < 2; ++k) dst[n][k] = *(const PG8_LAS bf16x8*)(lds + PG8_SB(b, h) + boff + n * 2048 + k * 1024); } while (0)
; #define PG8_WAIT_V(n) asm volatile("s_waitcnt vmcnt(" #n ")" ::: "memory")
; #define PG8_WAIT_L(n) asm volatile("s_waitcnt lgkmcnt(" #n ")" ::: "memory")
; #define PG8_BAR __builtin_amdgcn_s_barrier()
; #define PG8_SCHED __builtin_amdgcn_sched_barrier(0)
; template <class Epi, class Sched, bool ALIGN_EPI = false, bool SP2 = false>
; __device__ __forceinline__ void gemm_phase(PG8_LAS unsigned char* lds, const Gemm g, const Sched& S, const Epi& E) {
;     ...
;         const bool has_next = S.next(ui + 1, nxt);
;         const char* nA = has_next ? (const char*)g.A + (size_t)nxt.pm * tstep : cA; const char* nB = has_next ? (const char*)g.Bt + (size_t)nxt.pn * tstep : cB;
;         for (int t = 0; t < nt; t += 2) {
;             const bool last = (t == nt - 2);
;             const char* a1 = cA + (size_t)(t + 1) * kstep;
;             const char* a2 = last ? nA : cA + (size_t)(t + 2) * kstep; const char* b2 = last ? nB : cB + (size_t)(t + 2) * kstep;
;             const char* a3 = a2 + kstep; const char* b3 = b2 + kstep;
;             if (last && has_next) S.a_ready(nxt);
;             if constexpr (SP2) {
;             PG8_LDB(B0, 0, 0); PG8_LDB(B1, 0, 1); PG8_SCHED; PG8_LDA(At, 0, 0); PG8_STAGE(PG8_SA(1, 1), a1 + hstep, voffA);
;             PG8_WAIT_V(8); PG8_WAIT_L(0); PG8_BAR; PG8_MMA(0, 0, At, B0); PG8_MMA(0, 1, At, B1); PG8_BAR; PG8_SCHED;
;             PG8_LDA(At, 0, 1); PG8_STAGE(PG8_SB(0, 0), b2, voffB); PG8_STAGE(PG8_SB(0, 1), b2 + hstep, voffB); PG8_STAGE(PG8_SA(0, 0), a2, voffA);
;             PG8_WAIT_V(8); PG8_WAIT_L(0); PG8_BAR; PG8_MMA(1, 0, At, B0); PG8_MMA(1, 1, At, B1); PG8_BAR; PG8_SCHED;
.LBB0_448:
	s_add_u32 s48, s46, 0xfffc0080
	s_addc_u32 s49, s47, -1
	s_add_i32 s70, 0, 0x10000
	s_cmp_eq_u32 s69, 12
	s_cselect_b32 s53, s1, s49
	s_cselect_b32 s52, s37, s48
	v_add_u32_e32 v144, s70, v143
	s_cselect_b32 s49, s11, s68
	s_cselect_b32 s48, s66, s67
	s_add_i32 s72, 0, 0x14000
	ds_read_b128 v[148:151], v144
	ds_read_b128 v[152:155], v144 offset:1024
	ds_read_b128 v[156:159], v144 offset:2048
	ds_read_b128 v[192:195], v144 offset:3072
	v_add_u32_e32 v144, s72, v143
	ds_read_b128 v[196:199], v144
	ds_read_b128 v[200:203], v144 offset:1024
	ds_read_b128 v[204:207], v144 offset:2048
	ds_read_b128 v[208:211], v144 offset:3072
	v_lshl_add_u64 v[144:145], s[46:47], 0, v[138:139]
	s_add_i32 m0, s45, 0xc000
	ds_read_b128 v[212:215], v147
	ds_read_b128 v[216:219], v147 offset:1024
	ds_read_b128 v[220:223], v147 offset:2048
	ds_read_b128 v[224:227], v147 offset:3072
	ds_read_b128 v[228:231], v147 offset:4096
	ds_read_b128 v[232:235], v147 offset:5120
	ds_read_b128 v[236:239], v147 offset:6144
	ds_read_b128 v[240:243], v147 offset:7168
	global_load_lds_dwordx4 v[144:145], off
	v_lshl_add_u64 v[144:145], s[46:47], 0, v[140:141]
	s_add_i32 m0, s45, 0xe000
	s_nop 0
	global_load_lds_dwordx4 v[144:145], off
	s_waitcnt vmcnt(8)
	s_waitcnt lgkmcnt(0)
	s_barrier
	s_setprio 1
	s_waitcnt lgkmcnt(0)
	v_mfma_f32_16x16x32_bf16 v[126:129], v[148:151], v[212:215], v[126:129]
	v_mfma_f32_16x16x32_bf16 v[122:125], v[156:159], v[212:215], v[122:125]
	v_mfma_f32_16x16x32_bf16 v[114:117], v[148:151], v[220:223], v[114:117]
	v_mfma_f32_16x16x32_bf16 v[106:109], v[156:159], v[220:223], v[106:109]
	v_mfma_f32_16x16x32_bf16 v[98:101], v[148:151], v[228:231], v[98:101]
	v_mfma_f32_16x16x32_bf16 v[90:93], v[156:159], v[228:231], v[90:93]
	v_mfma_f32_16x16x32_bf16 v[82:85], v[148:151], v[236:239], v[82:85]
	v_mfma_f32_16x16x32_bf16 v[74:77], v[156:159], v[236:239], v[74:77]
	v_mfma_f32_16x16x32_bf16 v[126:129], v[152:155], v[216:219], v[126:129]
	v_mfma_f32_16x16x32_bf16 v[122:125], v[192:195], v[216:219], v[122:125]
	v_mfma_f32_16x16x32_bf16 v[114:117], v[152:155], v[224:227], v[114:117]
	v_mfma_f32_16x16x32_bf16 v[106:109], v[192:195], v[224:227], v[106:109]
	v_mfma_f32_16x16x32_bf16 v[98:101], v[152:155], v[232:235], v[98:101]
	v_mfma_f32_16x16x32_bf16 v[90:93], v[192:195], v[232:235], v[90:93]
	v_mfma_f32_16x16x32_bf16 v[82:85], v[152:155], v[240:243], v[82:85]
	v_mfma_f32_16x16x32_bf16 v[74:77], v[192:195], v[240:243], v[74:77]
	v_mfma_f32_16x16x32_bf16 v[118:121], v[196:199], v[212:215], v[118:121]
	v_mfma_f32_16x16x32_bf16 v[110:113], v[204:207], v[212:215], v[110:113]
	v_mfma_f32_16x16x32_bf16 v[102:105], v[196:199], v[220:223], v[102:105]
	v_mfma_f32_16x16x32_bf16 v[94:97], v[204:207], v[220:223], v[94:97]
	v_mfma_f32_16x16x32_bf16 v[86:89], v[196:199], v[228:231], v[86:89]
	v_mfma_f32_16x16x32_bf16 v[78:81], v[204:207], v[228:231], v[78:81]
	v_mfma_f32_16x16x32_bf16 v[70:73], v[196:199], v[236:239], v[70:73]
	v_mfma_f32_16x16x32_bf16 v[66:69], v[204:207], v[236:239], v[66:69]
	v_mfma_f32_16x16x32_bf16 v[118:121], v[200:203], v[216:219], v[118:121]
	v_mfma_f32_16x16x32_bf16 v[110:113], v[208:211], v[216:219], v[110:113]
	v_mfma_f32_16x16x32_bf16 v[102:105], v[200:203], v[224:227], v[102:105]
	v_mfma_f32_16x16x32_bf16 v[94:97], v[208:211], v[224:227], v[94:97]
	v_mfma_f32_16x16x32_bf16 v[86:89], v[200:203], v[232:235], v[86:89]
	v_mfma_f32_16x16x32_bf16 v[78:81], v[208:211], v[232:235], v[78:81]
	v_mfma_f32_16x16x32_bf16 v[70:73], v[200:203], v[240:243], v[70:73]
	v_mfma_f32_16x16x32_bf16 v[66:69], v[208:211], v[240:243], v[66:69]
	s_setprio 0
	s_barrier
	s_add_i32 s70, s70, s54
	v_lshl_add_u64 v[144:145], s[48:49], 0, v[134:135]
	s_mov_b32 m0, s70
	ds_read_b128 v[212:215], v147 offset:16384
	ds_read_b128 v[216:219], v147 offset:17408
	ds_read_b128 v[220:223], v147 offset:18432
	ds_read_b128 v[224:227], v147 offset:19456
	ds_read_b128 v[228:231], v147 offset:20480
	ds_read_b128 v[232:235], v147 offset:21504
	ds_read_b128 v[236:239], v147 offset:22528
	ds_read_b128 v[240:243], v147 offset:23552
	global_load_lds_dwordx4 v[144:145], off
	s_add_i32 m0, s70, 0x2000
	s_add_u32 s70, s48, 0x40000
	v_lshl_add_u64 v[160:161], s[48:49], 0, v[130:131]
	s_addc_u32 s71, s49, 0
	s_add_i32 s72, s72, s54
	global_load_lds_dwordx4 v[160:161], off
	v_lshl_add_u64 v[244:245], s[70:71], 0, v[134:135]
	s_mov_b32 m0, s72
	v_lshl_add_u64 v[246:247], s[52:53], 0, v[132:133]
	global_load_lds_dwordx4 v[244:245], off
	v_lshl_add_u64 v[244:245], s[70:71], 0, v[130:131]
	s_add_i32 m0, s72, 0x2000
	s_nop 0
	global_load_lds_dwordx4 v[244:245], off
	v_lshl_add_u64 v[244:245], s[52:53], 0, v[136:137]
	s_mov_b32 m0, s45
	s_nop 0
	global_load_lds_dwordx4 v[244:245], off
	s_mov_b32 m0, s60
	s_nop 0
	global_load_lds_dwordx4 v[246:247], off
	s_waitcnt vmcnt(8)
	s_waitcnt lgkmcnt(0)
	s_barrier
; #define PG8_STAGE(bufoff, gbase, voff) do { _Pragma("unroll") for (int _i = 0; _i < 2; ++_i) \
;         __builtin_amdgcn_global_load_lds((const unsigned*)((const char*)(gbase) + (voff)[_i]), (PG8_LAS unsigned*)(lds + (bufoff) + ldsw + _i * 8192), 16, 0, 0); } while (0)
; #define PG8_LDA(dst, b, h) do { _Pragma("unroll") for (int m = 0; m < 4; ++m) _Pragma("unroll") for (int k = 0; k < 2; ++k) dst[m][k] = *(const PG8_LAS bf16x8*)(lds + PG8_SA(b, h) + aoff + m * 2048 + k * 1024); } while (0)
; #define PG8_LDB(dst, b, h) do { _Pragma("unroll") for (int n = 0; n < 2; ++n) _Pragma("unroll") for (int k = 0; k < 2; ++k) dst[n][k] = *(const PG8_LAS bf16x8*)(lds + PG8_SB(b, h) + boff + n * 2048 + k * 1024); } while (0)
; #define PG8_MMA(ai, bj, At, Bt) do { __builtin_amdgcn_s_setprio(1); _Pragma("unroll") for (int m = 0; m < 4; ++m) _Pragma("unroll") for (int n = 0; n < 2; ++n) _Pragma("unroll") for (int k = 0; k < 2; ++k) \
;         acc[ai][bj][m][n] = __builtin_amdgcn_mfma_f32_16x16x32_bf16(Bt[n][k], At[m][k], acc[ai][bj][m][n], 0, 0, 0); __builtin_amdgcn_s_setprio(0); } while (0)
; #define PG8_WAIT_V(n) asm volatile("s_waitcnt vmcnt(" #n ")" ::: "memory")
; #define PG8_WAIT_L(n) asm volatile("s_waitcnt lgkmcnt(" #n ")" ::: "memory")
; #define PG8_BAR __builtin_amdgcn_s_barrier()
; #define PG8_SCHED __builtin_amdgcn_sched_barrier(0)
; template <class Epi, class Sched, bool ALIGN_EPI = false, bool SP2 = false>
; __device__ __forceinline__ void gemm_phase(PG8_LAS unsigned char* lds, const Gemm g, const Sched& S, const Epi& E) {
;     ...
;             PG8_WAIT_V(8); PG8_WAIT_L(0); PG8_BAR; PG8_MMA(1, 0, At, B0); PG8_MMA(1, 1, At, B1); PG8_BAR; PG8_SCHED;
;             PG8_LDB(B0, 1, 0); PG8_LDB(B1, 1, 1); PG8_SCHED; PG8_LDA(At, 1, 0); PG8_STAGE(PG8_SA(0, 1), a2 + hstep, voffA);
;             PG8_WAIT_V(8); PG8_WAIT_L(0); PG8_BAR; PG8_MMA(0, 0, At, B0); PG8_MMA(0, 1, At, B1); PG8_BAR; PG8_SCHED;
	s_setprio 1
	s_waitcnt lgkmcnt(0)
	v_mfma_f32_16x16x32_bf16 v[62:65], v[148:151], v[212:215], v[62:65]
	v_mfma_f32_16x16x32_bf16 v[58:61], v[156:159], v[212:215], v[58:61]
	v_mfma_f32_16x16x32_bf16 v[46:49], v[148:151], v[220:223], v[46:49]
	v_mfma_f32_16x16x32_bf16 v[42:45], v[156:159], v[220:223], v[42:45]
	v_mfma_f32_16x16x32_bf16 v[30:33], v[148:151], v[228:231], v[30:33]
	v_mfma_f32_16x16x32_bf16 v[26:29], v[156:159], v[228:231], v[26:29]
	v_mfma_f32_16x16x32_bf16 v[14:17], v[148:151], v[236:239], v[14:17]
	v_mfma_f32_16x16x32_bf16 v[10:13], v[156:159], v[236:239], v[10:13]
	v_mfma_f32_16x16x32_bf16 v[62:65], v[152:155], v[216:219], v[62:65]
	v_mfma_f32_16x16x32_bf16 v[58:61], v[192:195], v[216:219], v[58:61]
	v_mfma_f32_16x16x32_bf16 v[46:49], v[152:155], v[224:227], v[46:49]
	v_mfma_f32_16x16x32_bf16 v[42:45], v[192:195], v[224:227], v[42:45]
	v_mfma_f32_16x16x32_bf16 v[30:33], v[152:155], v[232:235], v[30:33]
	v_mfma_f32_16x16x32_bf16 v[26:29], v[192:195], v[232:235], v[26:29]
	v_mfma_f32_16x16x32_bf16 v[14:17], v[152:155], v[240:243], v[14:17]
	v_mfma_f32_16x16x32_bf16 v[10:13], v[192:195], v[240:243], v[10:13]
	v_mfma_f32_16x16x32_bf16 v[54:57], v[196:199], v[212:215], v[54:57]
	v_mfma_f32_16x16x32_bf16 v[50:53], v[204:207], v[212:215], v[50:53]
	v_mfma_f32_16x16x32_bf16 v[38:41], v[196:199], v[220:223], v[38:41]
	v_mfma_f32_16x16x32_bf16 v[34:37], v[204:207], v[220:223], v[34:37]
	v_mfma_f32_16x16x32_bf16 v[22:25], v[196:199], v[228:231], v[22:25]
	v_mfma_f32_16x16x32_bf16 v[18:21], v[204:207], v[228:231], v[18:21]
	v_mfma_f32_16x16x32_bf16 v[6:9], v[196:199], v[236:239], v[6:9]
	v_mfma_f32_16x16x32_bf16 v[2:5], v[204:207], v[236:239], v[2:5]
	v_mfma_f32_16x16x32_bf16 v[54:57], v[200:203], v[216:219], v[54:57]
	v_mfma_f32_16x16x32_bf16 v[50:53], v[208:211], v[216:219], v[50:53]
	v_mfma_f32_16x16x32_bf16 v[38:41], v[200:203], v[224:227], v[38:41]
	v_mfma_f32_16x16x32_bf16 v[34:37], v[208:211], v[224:227], v[34:37]
	v_mfma_f32_16x16x32_bf16 v[22:25], v[200:203], v[232:235], v[22:25]
	v_mfma_f32_16x16x32_bf16 v[18:21], v[208:211], v[232:235], v[18:21]
	v_mfma_f32_16x16x32_bf16 v[6:9], v[200:203], v[240:243], v[6:9]
	v_mfma_f32_16x16x32_bf16 v[2:5], v[208:211], v[240:243], v[2:5]
	s_setprio 0
	s_barrier
	s_add_i32 s70, 0, 0x18000
	s_add_i32 s71, 0, 0x1c000
	v_add_u32_e32 v192, s70, v143
	v_add_u32_e32 v208, s71, v143
	ds_read_b128 v[148:151], v192
	ds_read_b128 v[152:155], v192 offset:1024
	ds_read_b128 v[156:159], v192 offset:2048
	ds_read_b128 v[192:195], v192 offset:3072
	ds_read_b128 v[196:199], v208
	ds_read_b128 v[200:203], v208 offset:1024
	ds_read_b128 v[204:207], v208 offset:2048
	ds_read_b128 v[208:211], v208 offset:3072
	s_add_u32 s52, s52, 0x40000
	s_addc_u32 s53, s53, 0
	s_mov_b32 m0, s61
	v_lshl_add_u64 v[248:249], s[52:53], 0, v[136:137]
	ds_read_b128 v[212:215], v147 offset:32768
	ds_read_b128 v[216:219], v147 offset:33792
	ds_read_b128 v[220:223], v147 offset:34816
	ds_read_b128 v[224:227], v147 offset:35840
	ds_read_b128 v[228:231], v147 offset:36864
	ds_read_b128 v[232:235], v147 offset:37888
	ds_read_b128 v[236:239], v147 offset:38912
	ds_read_b128 v[240:243], v147 offset:39936
	global_load_lds_dwordx4 v[248:249], off
	v_lshl_add_u64 v[248:249], s[52:53], 0, v[132:133]
	s_mov_b32 m0, s62
	s_nop 0
	global_load_lds_dwordx4 v[248:249], off
	s_waitcnt vmcnt(8)
	s_waitcnt lgkmcnt(0)
	s_barrier
	s_setprio 1
	s_waitcnt lgkmcnt(0)
	v_mfma_f32_16x16x32_bf16 v[126:129], v[148:151], v[212:215], v[126:129]
	v_mfma_f32_16x16x32_bf16 v[122:125], v[156:159], v[212:215], v[122:125]
	v_mfma_f32_16x16x32_bf16 v[114:117], v[148:151], v[220:223], v[114:117]
	v_mfma_f32_16x16x32_bf16 v[106:109], v[156:159], v[220:223], v[106:109]
	v_mfma_f32_16x16x32_bf16 v[98:101], v[148:151], v[228:231], v[98:101]
	v_mfma_f32_16x16x32_bf16 v[90:93], v[156:159], v[228:231], v[90:93]
	v_mfma_f32_16x16x32_bf16 v[82:85], v[148:151], v[236:239], v[82:85]
	v_mfma_f32_16x16x32_bf16 v[74:77], v[156:159], v[236:239], v[74:77]
	v_mfma_f32_16x16x32_bf16 v[126:129], v[152:155], v[216:219], v[126:129]
	v_mfma_f32_16x16x32_bf16 v[122:125], v[192:195], v[216:219], v[122:125]
	v_mfma_f32_16x16x32_bf16 v[114:117], v[152:155], v[224:227], v[114:117]
	v_mfma_f32_16x16x32_bf16 v[106:109], v[192:195], v[224:227], v[106:109]
	v_mfma_f32_16x16x32_bf16 v[98:101], v[152:155], v[232:235], v[98:101]
	v_mfma_f32_16x16x32_bf16 v[90:93], v[192:195], v[232:235], v[90:93]
	v_mfma_f32_16x16x32_bf16 v[82:85], v[152:155], v[240:243], v[82:85]
	v_mfma_f32_16x16x32_bf16 v[74:77], v[192:195], v[240:243], v[74:77]
	v_mfma_f32_16x16x32_bf16 v[118:121], v[196:199], v[212:215], v[118:121]
	v_mfma_f32_16x16x32_bf16 v[110:113], v[204:207], v[212:215], v[110:113]
	v_mfma_f32_16x16x32_bf16 v[102:105], v[196:199], v[220:223], v[102:105]
	v_mfma_f32_16x16x32_bf16 v[94:97], v[204:207], v[220:223], v[94:97]
	v_mfma_f32_16x16x32_bf16 v[86:89], v[196:199], v[228:231], v[86:89]
	v_mfma_f32_16x16x32_bf16 v[78:81], v[204:207], v[228:231], v[78:81]
	v_mfma_f32_16x16x32_bf16 v[70:73], v[196:199], v[236:239], v[70:73]
	v_mfma_f32_16x16x32_bf16 v[66:69], v[204:207], v[236:239], v[66:69]
	v_mfma_f32_16x16x32_bf16 v[118:121], v[200:203], v[216:219], v[118:121]
	v_mfma_f32_16x16x32_bf16 v[110:113], v[208:211], v[216:219], v[110:113]
	v_mfma_f32_16x16x32_bf16 v[102:105], v[200:203], v[224:227], v[102:105]
	v_mfma_f32_16x16x32_bf16 v[94:97], v[208:211], v[224:227], v[94:97]
	v_mfma_f32_16x16x32_bf16 v[86:89], v[200:203], v[232:235], v[86:89]
	v_mfma_f32_16x16x32_bf16 v[78:81], v[208:211], v[232:235], v[78:81]
	v_mfma_f32_16x16x32_bf16 v[70:73], v[200:203], v[240:243], v[70:73]
	v_mfma_f32_16x16x32_bf16 v[66:69], v[208:211], v[240:243], v[66:69]
	s_setprio 0
	s_barrier
; #define PG8_STAGE(bufoff, gbase, voff) do { _Pragma("unroll") for (int _i = 0; _i < 2; ++_i) \
;         __builtin_amdgcn_global_load_lds((const unsigned*)((const char*)(gbase) + (voff)[_i]), (PG8_LAS unsigned*)(lds + (bufoff) + ldsw + _i * 8192), 16, 0, 0); } while (0)
; #define PG8_LDA(dst, b, h) do { _Pragma("unroll") for (int m = 0; m < 4; ++m) _Pragma("unroll") for (int k = 0; k < 2; ++k) dst[m][k] = *(const PG8_LAS bf16x8*)(lds + PG8_SA(b, h) + aoff + m * 2048 + k * 1024); } while (0)
; #define PG8_MMA(ai, bj, At, Bt) do { __builtin_amdgcn_s_setprio(1); _Pragma("unroll") for (int m = 0; m < 4; ++m) _Pragma("unroll") for (int n = 0; n < 2; ++n) _Pragma("unroll") for (int k = 0; k < 2; ++k) \
;         acc[ai][bj][m][n] = __builtin_amdgcn_mfma_f32_16x16x32_bf16(Bt[n][k], At[m][k], acc[ai][bj][m][n], 0, 0, 0); __builtin_amdgcn_s_setprio(0); } while (0)
; #define PG8_WAIT_V(n) asm volatile("s_waitcnt vmcnt(" #n ")" ::: "memory")
; #define PG8_WAIT_L(n) asm volatile("s_waitcnt lgkmcnt(" #n ")" ::: "memory")
; #define PG8_BAR __builtin_amdgcn_s_barrier()
; #define PG8_SCHED __builtin_amdgcn_sched_barrier(0)
; template <class Epi, class Sched, bool ALIGN_EPI = false, bool SP2 = false>
; __device__ __forceinline__ void gemm_phase(PG8_LAS unsigned char* lds, const Gemm g, const Sched& S, const Epi& E) {
;     ...
;         for (int t = 0; t < nt; t += 2) {
;     ...
;             PG8_LDA(At, 1, 1); PG8_STAGE(PG8_SB(1, 0), b3, voffB); PG8_STAGE(PG8_SB(1, 1), b3 + hstep, voffB); PG8_STAGE(PG8_SA(1, 0), a3, voffA);
;             PG8_WAIT_V(8); PG8_WAIT_L(0); PG8_BAR; PG8_MMA(1, 0, At, B0); PG8_MMA(1, 1, At, B1); PG8_BAR; PG8_SCHED;
;     ...
;         if constexpr (ALIGN_EPI) { if (wr == 0) PG8_BAR; }
	s_add_i32 s52, s70, s54
	v_lshl_add_u64 v[144:145], v[144:145], 0, s[28:29]
	s_mov_b32 m0, s52
	ds_read_b128 v[212:215], v147 offset:49152
	ds_read_b128 v[216:219], v147 offset:50176
	ds_read_b128 v[220:223], v147 offset:51200
	ds_read_b128 v[224:227], v147 offset:52224
	ds_read_b128 v[228:231], v147 offset:53248
	ds_read_b128 v[232:235], v147 offset:54272
	ds_read_b128 v[236:239], v147 offset:55296
	ds_read_b128 v[240:243], v147 offset:56320
	global_load_lds_dwordx4 v[144:145], off
	s_add_i32 m0, s52, 0x2000
	s_add_u32 s48, s48, 0x40080
	v_lshl_add_u64 v[144:145], v[160:161], 0, s[28:29]
	s_addc_u32 s49, s49, 0
	s_add_i32 s52, s71, s54
	global_load_lds_dwordx4 v[144:145], off
	v_lshl_add_u64 v[144:145], s[48:49], 0, v[134:135]
	s_mov_b32 m0, s52
	s_nop 0
	global_load_lds_dwordx4 v[144:145], off
	v_lshl_add_u64 v[144:145], s[48:49], 0, v[130:131]
	s_add_i32 m0, s52, 0x2000
	s_nop 0
	global_load_lds_dwordx4 v[144:145], off
	v_lshl_add_u64 v[144:145], v[244:245], 0, s[28:29]
	s_mov_b32 m0, s50
	s_nop 0
	global_load_lds_dwordx4 v[144:145], off
	v_lshl_add_u64 v[144:145], v[246:247], 0, s[28:29]
	s_mov_b32 m0, s51
	s_nop 0
	global_load_lds_dwordx4 v[144:145], off
	s_waitcnt vmcnt(8)
	s_waitcnt lgkmcnt(0)
	s_barrier
	s_setprio 1
	s_waitcnt lgkmcnt(0)
	v_mfma_f32_16x16x32_bf16 v[62:65], v[148:151], v[212:215], v[62:65]
	v_mfma_f32_16x16x32_bf16 v[58:61], v[156:159], v[212:215], v[58:61]
	v_mfma_f32_16x16x32_bf16 v[46:49], v[148:151], v[220:223], v[46:49]
	v_mfma_f32_16x16x32_bf16 v[42:45], v[156:159], v[220:223], v[42:45]
	v_mfma_f32_16x16x32_bf16 v[30:33], v[148:151], v[228:231], v[30:33]
	v_mfma_f32_16x16x32_bf16 v[26:29], v[156:159], v[228:231], v[26:29]
	v_mfma_f32_16x16x32_bf16 v[14:17], v[148:151], v[236:239], v[14:17]
	v_mfma_f32_16x16x32_bf16 v[10:13], v[156:159], v[236:239], v[10:13]
	v_mfma_f32_16x16x32_bf16 v[62:65], v[152:155], v[216:219], v[62:65]
	v_mfma_f32_16x16x32_bf16 v[58:61], v[192:195], v[216:219], v[58:61]
	v_mfma_f32_16x16x32_bf16 v[46:49], v[152:155], v[224:227], v[46:49]
	v_mfma_f32_16x16x32_bf16 v[42:45], v[192:195], v[224:227], v[42:45]
	v_mfma_f32_16x16x32_bf16 v[30:33], v[152:155], v[232:235], v[30:33]
	v_mfma_f32_16x16x32_bf16 v[26:29], v[192:195], v[232:235], v[26:29]
	v_mfma_f32_16x16x32_bf16 v[14:17], v[152:155], v[240:243], v[14:17]
	v_mfma_f32_16x16x32_bf16 v[10:13], v[192:195], v[240:243], v[10:13]
	v_mfma_f32_16x16x32_bf16 v[54:57], v[196:199], v[212:215], v[54:57]
	v_mfma_f32_16x16x32_bf16 v[50:53], v[204:207], v[212:215], v[50:53]
	v_mfma_f32_16x16x32_bf16 v[38:41], v[196:199], v[220:223], v[38:41]
	v_mfma_f32_16x16x32_bf16 v[34:37], v[204:207], v[220:223], v[34:37]
	v_mfma_f32_16x16x32_bf16 v[22:25], v[196:199], v[228:231], v[22:25]
	v_mfma_f32_16x16x32_bf16 v[18:21], v[204:207], v[228:231], v[18:21]
	v_mfma_f32_16x16x32_bf16 v[6:9], v[196:199], v[236:239], v[6:9]
	v_mfma_f32_16x16x32_bf16 v[2:5], v[204:207], v[236:239], v[2:5]
	v_mfma_f32_16x16x32_bf16 v[54:57], v[200:203], v[216:219], v[54:57]
	v_mfma_f32_16x16x32_bf16 v[50:53], v[208:211], v[216:219], v[50:53]
	v_mfma_f32_16x16x32_bf16 v[38:41], v[200:203], v[224:227], v[38:41]
	v_mfma_f32_16x16x32_bf16 v[34:37], v[208:211], v[224:227], v[34:37]
	v_mfma_f32_16x16x32_bf16 v[22:25], v[200:203], v[232:235], v[22:25]
	v_mfma_f32_16x16x32_bf16 v[18:21], v[208:211], v[232:235], v[18:21]
	v_mfma_f32_16x16x32_bf16 v[6:9], v[200:203], v[240:243], v[6:9]
	v_mfma_f32_16x16x32_bf16 v[2:5], v[208:211], v[240:243], v[2:5]
	s_setprio 0
	s_barrier
	s_add_i32 s69, s69, 2
	s_add_u32 s46, s46, 0x100
	s_addc_u32 s47, s47, 0
	s_add_u32 s67, s67, 0x100
	s_addc_u32 s68, s68, 0
	s_cmp_gt_u32 s69, 13
	s_cbranch_scc0 .LBB0_448
	s_and_b64 vcc, exec, s[8:9]
	s_cbranch_vccz .LBB0_451
	s_barrier
